# norm1/norm2 row loops: next row's 4 x dwordx4 loads software-prefetched into a second register set (was 1-2 exposed memory latencies per row)
# speedup vs baseline: 1.0142x; 1.0122x over previous
.LBB0_84:
	v_writelane_b32 v255, s56, 10
	s_nop 1
	v_writelane_b32 v255, s57, 11
	v_writelane_b32 v255, s54, 12
	s_nop 1
	v_writelane_b32 v255, s55, 13
	v_writelane_b32 v255, s31, 21
	v_writelane_b32 v255, s30, 20
	s_or_b64 exec, exec, s[2:3]
	v_readlane_b32 s52, v252, 0
	v_mov_b32_e32 v17, v216
	s_lshl_b64 s[4:5], s[8:9], 2
	v_readlane_b32 s62, v252, 10
	s_barrier
	v_readlane_b32 s63, v252, 11
	v_and_b32_e32 v16, 63, v17
	s_add_u32 s2, s62, s4
	v_writelane_b32 v255, s4, 26
	s_addc_u32 s3, s63, s5
	v_lshlrev_b32_e32 v12, 4, v16
	v_writelane_b32 v255, s5, 27
	global_load_dwordx4 v[0:3], v12, s[2:3]
	global_load_dwordx4 v[4:7], v12, s[2:3] offset:1024
	global_load_dwordx4 v[8:11], v12, s[2:3] offset:2048
	s_nop 0
	global_load_dwordx4 v[12:15], v12, s[2:3] offset:3072
	v_readlane_b32 s2, v255, 18
	v_readlane_b32 s3, v255, 19
	s_mul_i32 s94, s2, 0x642000
	v_readlane_b32 s64, v252, 12
	s_lshl_b64 s[2:3], s[94:95], 2
	v_readlane_b32 s65, v252, 13
	s_add_u32 s2, s64, s2
	s_addc_u32 s3, s65, s3
	s_add_u32 s2, s2, 0x1000
	s_addc_u32 s3, s3, 0
	s_waitcnt vmcnt(20)
	v_mov_b64_e32 v[34:35], s[2:3]
	v_add_u32_e32 v26, 0x100, v17
	v_mad_i64_i32 v[22:23], s[2:3], v17, s18, v[34:35]
	v_mad_i64_i32 v[30:31], s[2:3], v26, s18, v[34:35]
	global_load_dwordx4 v[18:21], v[22:23], off offset:16
	s_nop 0
	global_load_dwordx4 v[22:25], v[22:23], off
	s_nop 0
	global_load_dwordx4 v[26:29], v[30:31], off offset:16
	s_nop 0
	global_load_dwordx4 v[30:33], v[30:31], off
	s_waitcnt vmcnt(22)
	v_lshlrev_b32_e32 v37, 2, v17
	v_ashrrev_i32_e32 v36, 6, v17
	v_readlane_b32 s53, v252, 1
	v_readlane_b32 s54, v252, 2
	v_readlane_b32 s55, v252, 3
	v_readlane_b32 s56, v252, 4
	v_readlane_b32 s57, v252, 5
	v_readlane_b32 s58, v252, 6
	v_readlane_b32 s59, v252, 7
	v_readlane_b32 s60, v252, 8
	v_readlane_b32 s61, v252, 9
	v_readlane_b32 s66, v252, 14
	v_readlane_b32 s67, v252, 15
	s_waitcnt vmcnt(0)
	ds_write2st64_b32 v37, v22, v30 offset1:4
	ds_write2st64_b32 v37, v23, v31 offset0:16 offset1:20
	ds_write2st64_b32 v37, v24, v32 offset0:32 offset1:36
	ds_write2st64_b32 v37, v25, v33 offset0:48 offset1:52
	ds_write2st64_b32 v37, v18, v26 offset0:64 offset1:68
	ds_write2st64_b32 v37, v19, v27 offset0:80 offset1:84
	ds_write2st64_b32 v37, v20, v28 offset0:96 offset1:100
	ds_write2st64_b32 v37, v21, v29 offset0:112 offset1:116
	v_add_u32_e32 v18, 0x200, v17
	v_add_u32_e32 v17, 0x300, v17
	v_mad_i64_i32 v[22:23], s[2:3], v18, s18, v[34:35]
	v_mad_i64_i32 v[30:31], s[2:3], v17, s18, v[34:35]
	global_load_dwordx4 v[18:21], v[22:23], off offset:16
	s_nop 0
	global_load_dwordx4 v[22:25], v[22:23], off
	s_nop 0
	global_load_dwordx4 v[26:29], v[30:31], off offset:16
	s_nop 0
	global_load_dwordx4 v[30:33], v[30:31], off
	v_readlane_b32 s2, v253, 8
	s_waitcnt vmcnt(0)
	ds_write2st64_b32 v37, v22, v30 offset0:8 offset1:12
	ds_write2st64_b32 v37, v23, v31 offset0:24 offset1:28
	ds_write2st64_b32 v37, v24, v32 offset0:40 offset1:44
	ds_write2st64_b32 v37, v25, v33 offset0:56 offset1:60
	ds_write2st64_b32 v37, v18, v26 offset0:72 offset1:76
	ds_write2st64_b32 v37, v19, v27 offset0:88 offset1:92
	ds_write2st64_b32 v37, v20, v28 offset0:104 offset1:108
	ds_write2st64_b32 v37, v21, v29 offset0:120 offset1:124
	v_add_u32_e32 v128, s2, v36
	s_movk_i32 s2, 0x4480
	v_cmp_gt_i32_e32 vcc, s2, v128
	s_waitcnt lgkmcnt(0)
	s_barrier
	s_and_saveexec_b64 s[2:3], vcc
	s_cbranch_execz .LBB0_112
	v_cmp_lt_i32_e32 vcc, v227, v219
	v_lshlrev_b32_e32 v17, 2, v16
	v_readlane_b32 s4, v253, 4
	v_cndmask_b32_e32 v18, v218, v227, vcc
	v_cmp_lt_i32_e32 vcc, v225, v219
	v_lshlrev_b32_e32 v168, 2, v18
	v_lshlrev_b32_e32 v200, 1, v17
	v_cndmask_b32_e32 v18, v218, v225, vcc
	v_cmp_lt_i32_e32 vcc, v223, v219
	v_lshlrev_b32_e32 v169, 2, v18
	v_readlane_b32 s5, v253, 5
	v_cndmask_b32_e32 v18, v218, v223, vcc
	v_cmp_lt_i32_e32 vcc, v222, v219
	v_lshlrev_b32_e32 v170, 2, v18
	v_lshl_add_u64 v[130:131], s[4:5], 0, v[200:201]
	v_cndmask_b32_e32 v18, v218, v222, vcc
	v_cmp_lt_i32_e32 vcc, v221, v219
	v_lshlrev_b32_e32 v171, 2, v18
	v_lshlrev_b32_e32 v200, 2, v17
	v_cndmask_b32_e32 v18, v218, v221, vcc
	v_cmp_lt_i32_e32 vcc, v220, v219
	v_lshlrev_b32_e32 v172, 2, v18
	v_readlane_b32 s4, v253, 6
	v_cndmask_b32_e32 v18, v218, v220, vcc
	v_lshlrev_b32_e32 v173, 2, v18
	v_cmp_eq_u32_e32 vcc, 0, v16
	ds_read_b128 v[124:127], v200
	ds_read_b128 v[16:19], v200 offset:1024
	ds_read_b128 v[20:23], v200 offset:4096
	ds_read_b128 v[24:27], v200 offset:5120
	ds_read_b128 v[28:31], v200 offset:8192
	ds_read_b128 v[32:35], v200 offset:9216
	ds_read_b128 v[36:39], v200 offset:12288
	ds_read_b128 v[40:43], v200 offset:13312
	ds_read_b128 v[44:47], v200 offset:16384
	ds_read_b128 v[48:51], v200 offset:17408
	ds_read_b128 v[52:55], v200 offset:20480
	ds_read_b128 v[56:59], v200 offset:21504
	ds_read_b128 v[60:63], v200 offset:24576
	ds_read_b128 v[64:67], v200 offset:25600
	ds_read_b128 v[68:71], v200 offset:28672
	ds_read_b128 v[72:75], v200 offset:29696
	ds_read_b128 v[162:165], v200 offset:2048
	ds_read_b128 v[76:79], v200 offset:3072
	ds_read_b128 v[80:83], v200 offset:6144
	ds_read_b128 v[84:87], v200 offset:7168
	ds_read_b128 v[174:177], v200 offset:10240
	ds_read_b128 v[88:91], v200 offset:11264
	ds_read_b128 v[92:95], v200 offset:14336
	ds_read_b128 v[96:99], v200 offset:15360
	ds_read_b128 v[178:181], v200 offset:18432
	ds_read_b128 v[100:103], v200 offset:19456
	ds_read_b128 v[104:107], v200 offset:22528
	ds_read_b128 v[108:111], v200 offset:23552
	ds_read_b128 v[182:185], v200 offset:26624
	ds_read_b128 v[112:115], v200 offset:27648
	ds_read_b128 v[116:119], v200 offset:30720
	ds_read_b128 v[120:123], v200 offset:31744
	v_readlane_b32 s5, v253, 7
	s_waitcnt lgkmcnt(14)
	v_mov_b32_e32 v134, v19
	v_mov_b32_e32 v135, v27
	v_lshl_add_u64 v[132:133], s[4:5], 0, v[200:201]
	v_mov_b32_e32 v136, v164
	s_waitcnt lgkmcnt(13)
	v_mov_b32_e32 v137, v82
	v_mov_b32_e32 v82, v165
	s_waitcnt lgkmcnt(12)
	v_pk_mov_b32 v[138:139], v[76:77], v[84:85] op_sel:[1,0]
	v_mov_b32_e32 v140, v78
	v_mov_b32_e32 v141, v86
	v_mov_b32_e32 v86, v79
	v_mov_b32_e32 v78, v35
	v_mov_b32_e32 v79, v43
	s_waitcnt lgkmcnt(11)
	v_mov_b32_e32 v142, v176
	s_waitcnt lgkmcnt(9)
	v_mov_b32_e32 v143, v94
	v_mov_b32_e32 v94, v177
	s_waitcnt lgkmcnt(8)
	v_pk_mov_b32 v[144:145], v[88:89], v[96:97] op_sel:[1,0]
	v_mov_b32_e32 v146, v90
	v_mov_b32_e32 v147, v98
	v_mov_b32_e32 v98, v91
	v_mov_b32_e32 v90, v51
	v_mov_b32_e32 v91, v59
	s_waitcnt lgkmcnt(7)
	v_mov_b32_e32 v148, v180
	s_waitcnt lgkmcnt(5)
	v_mov_b32_e32 v149, v106
	v_mov_b32_e32 v106, v181
	s_waitcnt lgkmcnt(4)
	v_pk_mov_b32 v[150:151], v[100:101], v[108:109] op_sel:[1,0]
	v_mov_b32_e32 v152, v102
	v_mov_b32_e32 v153, v110
	v_mov_b32_e32 v110, v103
	v_mov_b32_e32 v102, v67
	v_mov_b32_e32 v103, v75
	s_waitcnt lgkmcnt(3)
	v_mov_b32_e32 v154, v184
	s_waitcnt lgkmcnt(1)
	v_mov_b32_e32 v155, v118
	v_mov_b32_e32 v118, v185
	s_waitcnt lgkmcnt(0)
	v_pk_mov_b32 v[156:157], v[112:113], v[120:121] op_sel:[1,0]
	v_mov_b32_e32 v158, v114
	v_mov_b32_e32 v159, v122
	v_mov_b32_e32 v122, v115
	v_mov_b32_e32 v114, v1
	v_mov_b32_e32 v115, v3
	v_mov_b32_e32 v1, v2
	v_mov_b32_e32 v2, v5
	v_mov_b32_e32 v3, v7
	v_mov_b32_e32 v5, v6
	v_mov_b32_e32 v6, v9
	v_mov_b32_e32 v7, v11
	v_mov_b32_e32 v9, v10
	v_mov_b32_e32 v10, v13
	v_mov_b32_e32 v11, v15
	v_mov_b32_e32 v13, v14
	v_mov_b32_e32 v14, v182
	v_mov_b32_e32 v15, v117
	v_mov_b32_e32 v160, v183
	v_mov_b32_e32 v161, v116
	v_mov_b32_e32 v67, v74
	v_mov_b32_e32 v74, v64
	v_mov_b32_e32 v75, v72
	v_mov_b32_e32 v72, v65
	v_mov_b32_e32 v64, v63
	v_mov_b32_e32 v65, v71
	v_mov_b32_e32 v116, v60
	v_mov_b32_e32 v117, v68
	v_mov_b32_e32 v68, v61
	v_mov_b32_e32 v63, v70
	v_mov_b32_e32 v60, v178
	v_mov_b32_e32 v61, v105
	v_mov_b32_e32 v70, v179
	v_mov_b32_e32 v71, v104
	v_mov_b32_e32 v51, v58
	v_mov_b32_e32 v58, v48
	v_mov_b32_e32 v59, v56
	v_mov_b32_e32 v56, v49
	v_mov_b32_e32 v48, v47
	v_mov_b32_e32 v49, v55
	v_mov_b32_e32 v104, v44
	v_mov_b32_e32 v105, v52
	v_mov_b32_e32 v52, v45
	v_mov_b32_e32 v47, v54
	v_mov_b32_e32 v44, v174
	v_mov_b32_e32 v45, v93
	v_mov_b32_e32 v54, v175
	v_mov_b32_e32 v55, v92
	v_mov_b32_e32 v35, v42
	v_mov_b32_e32 v42, v32
	v_mov_b32_e32 v43, v40
	v_mov_b32_e32 v40, v33
	v_mov_b32_e32 v32, v31
	v_mov_b32_e32 v33, v39
	v_mov_b32_e32 v92, v28
	v_mov_b32_e32 v93, v36
	v_mov_b32_e32 v36, v29
	v_mov_b32_e32 v31, v38
	v_mov_b32_e32 v28, v162
	v_mov_b32_e32 v29, v81
	v_mov_b32_e32 v38, v163
	v_mov_b32_e32 v39, v80
	v_mov_b32_e32 v19, v26
	v_mov_b32_e32 v26, v16
	v_mov_b32_e32 v27, v24
	v_mov_b32_e32 v24, v17
	v_mov_b32_e32 v16, v126
	v_mov_b32_e32 v17, v22
	v_mov_b32_e32 v80, v124
	v_mov_b32_e32 v81, v20
	v_mov_b32_e32 v20, v125
	v_mov_b32_e32 v22, v127
	v_mov_b32_e32 v77, v85
	v_mov_b32_e32 v89, v97
	v_mov_b32_e32 v101, v109
	v_mov_b32_e32 v113, v121
	s_mov_b64 s[4:5], 0
	v_mov_b32_e32 v212, v128
	v_ashrrev_i32_e32 v213, 31, v212
	v_lshlrev_b64 v[212:213], 12, v[212:213]
	v_lshl_add_u64 v[212:213], v[132:133], 0, v[212:213]
	global_load_dwordx4 v[192:195], v[212:213], off
	global_load_dwordx4 v[196:199], v[212:213], off offset:1024
	global_load_dwordx4 v[204:207], v[212:213], off offset:2048
	global_load_dwordx4 v[208:211], v[212:213], off offset:3072
	s_branch .LBB0_87

.LBB0_87:
	v_ashrrev_i32_e32 v129, 31, v128
	v_lshlrev_b64 v[84:85], 12, v[128:129]
	v_lshl_add_u64 v[84:85], v[132:133], 0, v[84:85]
	s_waitcnt lgkmcnt(2)
	s_waitcnt vmcnt(0)
	v_mov_b32_e32 v124, v192
	v_mov_b32_e32 v125, v193
	v_mov_b32_e32 v126, v194
	v_mov_b32_e32 v127, v195
	s_waitcnt lgkmcnt(0)
	v_mov_b32_e32 v164, v196
	v_mov_b32_e32 v165, v197
	v_mov_b32_e32 v166, v198
	v_mov_b32_e32 v167, v199
	v_mov_b32_e32 v174, v204
	v_mov_b32_e32 v175, v205
	v_mov_b32_e32 v176, v206
	v_mov_b32_e32 v177, v207
	v_mov_b32_e32 v178, v208
	v_mov_b32_e32 v179, v209
	v_mov_b32_e32 v180, v210
	v_mov_b32_e32 v181, v211
	v_add_u32_e32 v212, s81, v128
	v_min_i32_e32 v212, s76, v212
	v_ashrrev_i32_e32 v213, 31, v212
	v_lshlrev_b64 v[212:213], 12, v[212:213]
	v_lshl_add_u64 v[212:213], v[132:133], 0, v[212:213]
	global_load_dwordx4 v[192:195], v[212:213], off
	global_load_dwordx4 v[196:199], v[212:213], off offset:1024
	global_load_dwordx4 v[204:207], v[212:213], off offset:2048
	global_load_dwordx4 v[208:211], v[212:213], off offset:3072
	v_mov_b32_e32 v96, v125
	v_mov_b32_e32 v97, v165
	v_mov_b32_e32 v84, v124
	v_mov_b32_e32 v85, v164
	v_mov_b32_e32 v182, v175
	v_mov_b32_e32 v183, v179
	v_pk_mul_f32 v[96:97], v[96:97], v[96:97]
	v_mov_b32_e32 v108, v126
	v_mov_b32_e32 v109, v166
	v_mov_b32_e32 v162, v174
	v_mov_b32_e32 v163, v178
	v_pk_mul_f32 v[182:183], v[182:183], v[182:183]
	v_pk_fma_f32 v[84:85], v[84:85], v[84:85], v[96:97]
	v_mov_b32_e32 v120, v127
	v_mov_b32_e32 v121, v167
	v_mov_b32_e32 v184, v176
	v_mov_b32_e32 v185, v180
	v_pk_fma_f32 v[96:97], v[162:163], v[162:163], v[182:183]
	v_pk_fma_f32 v[84:85], v[108:109], v[108:109], v[84:85]
	v_mov_b32_e32 v186, v177
	v_mov_b32_e32 v187, v181
	v_pk_fma_f32 v[96:97], v[184:185], v[184:185], v[96:97]
	v_pk_fma_f32 v[84:85], v[120:121], v[120:121], v[84:85]
	v_pk_fma_f32 v[96:97], v[186:187], v[186:187], v[96:97]
	v_add_f32_e32 v84, v84, v85
	v_add_f32_e32 v84, v84, v96
	v_add_f32_e32 v84, v84, v97
	ds_bpermute_b32 v85, v168, v84
	v_mov_b32_e32 v108, v125
	v_mov_b32_e32 v121, v166
	v_mov_b32_e32 v166, v165
	s_waitcnt lgkmcnt(0)
	v_add_f32_e32 v84, v84, v85
	ds_bpermute_b32 v85, v169, v84
	s_waitcnt lgkmcnt(0)
	v_add_f32_e32 v96, v84, v85
	ds_bpermute_b32 v97, v170, v96
	v_lshlrev_b64 v[84:85], 11, v[128:129]
	v_lshl_add_u64 v[84:85], v[130:131], 0, v[84:85]
	s_waitcnt lgkmcnt(0)
	v_add_f32_e32 v109, v96, v97
	ds_bpermute_b32 v120, v171, v109
	v_mov_b32_e32 v96, v124
	v_mov_b32_e32 v97, v126
	s_waitcnt lgkmcnt(0)
	v_add_f32_e32 v124, v109, v120
	ds_bpermute_b32 v125, v172, v124
	v_mov_b32_e32 v109, v127
	v_mov_b32_e32 v120, v164
	s_waitcnt lgkmcnt(0)
	v_add_f32_e32 v126, v124, v125
	ds_bpermute_b32 v127, v173, v126
	v_mov_b32_e32 v124, v174
	v_mov_b32_e32 v125, v176
	v_mov_b32_e32 v174, v175
	v_mov_b32_e32 v175, v177
	s_waitcnt lgkmcnt(0)
	v_add_f32_e32 v126, v126, v127
	v_fmamk_f32 v126, v126, 0x3a800000, v217
	v_mul_f32_e32 v127, 0x4b800000, v126
	v_cmp_gt_f32_e64 s[8:9], s75, v126
	v_mov_b32_e32 v176, v178
	v_mov_b32_e32 v177, v180
	v_cndmask_b32_e64 v126, v126, v127, s[8:9]
	v_rsq_f32_e32 v126, v126
	v_mov_b32_e32 v180, v179
	v_mul_f32_e32 v127, 0x45800000, v126
	v_cndmask_b32_e64 v126, v126, v127, s[8:9]
	v_pk_mul_f32 v[162:163], v[0:1], v[126:127] op_sel_hi:[1,0]
	v_pk_mul_f32 v[164:165], v[114:115], v[126:127] op_sel_hi:[1,0]
	v_pk_mul_f32 v[178:179], v[4:5], v[126:127] op_sel_hi:[1,0]
	v_pk_mul_f32 v[182:183], v[2:3], v[126:127] op_sel_hi:[1,0]
	v_pk_mul_f32 v[186:187], v[96:97], v[162:163]
	v_pk_mul_f32 v[96:97], v[6:7], v[126:127] op_sel_hi:[1,0]
	v_pk_mul_f32 v[164:165], v[108:109], v[164:165]
	v_pk_mul_f32 v[108:109], v[12:13], v[126:127] op_sel_hi:[1,0]
	v_pk_mul_f32 v[188:189], v[10:11], v[126:127] op_sel_hi:[1,0]
	v_pk_mul_f32 v[184:185], v[8:9], v[126:127] op_sel_hi:[1,0]
	v_pk_mul_f32 v[162:163], v[120:121], v[178:179]
	v_pk_mul_f32 v[126:127], v[166:167], v[182:183]
	v_pk_mul_f32 v[120:121], v[174:175], v[96:97]
	v_pk_mul_f32 v[96:97], v[176:177], v[108:109]
	v_pk_mul_f32 v[108:109], v[180:181], v[188:189]
	v_and_b32_sdwa v181, v186, v232 dst_sel:DWORD dst_unused:UNUSED_PAD src0_sel:WORD_1 src1_sel:DWORD
	v_and_b32_sdwa v182, v165, v232 dst_sel:DWORD dst_unused:UNUSED_PAD src0_sel:WORD_1 src1_sel:DWORD
	v_and_b32_sdwa v183, v164, v232 dst_sel:DWORD dst_unused:UNUSED_PAD src0_sel:WORD_1 src1_sel:DWORD
	v_and_b32_sdwa v180, v187, v232 dst_sel:DWORD dst_unused:UNUSED_PAD src0_sel:WORD_1 src1_sel:DWORD
	v_pk_mul_f32 v[166:167], v[20:21], v[164:165] op_sel_hi:[1,0]
	v_pk_mul_f32 v[174:175], v[164:165], v[36:37] op_sel_hi:[0,1]
	v_pk_mul_f32 v[176:177], v[164:165], v[52:53] op_sel_hi:[0,1]
	v_pk_mul_f32 v[178:179], v[164:165], v[68:69] op_sel_hi:[0,1]
	v_add3_u32 v190, v186, v181, s69
	v_add3_u32 v181, v165, v182, s69
	v_add3_u32 v182, v164, v183, s69
	v_pk_mul_f32 v[124:125], v[124:125], v[184:185]
	v_and_b32_sdwa v184, v163, v232 dst_sel:DWORD dst_unused:UNUSED_PAD src0_sel:WORD_1 src1_sel:DWORD
	v_and_b32_sdwa v185, v162, v232 dst_sel:DWORD dst_unused:UNUSED_PAD src0_sel:WORD_1 src1_sel:DWORD
	v_and_b32_sdwa v188, v127, v232 dst_sel:DWORD dst_unused:UNUSED_PAD src0_sel:WORD_1 src1_sel:DWORD
	v_and_b32_sdwa v189, v126, v232 dst_sel:DWORD dst_unused:UNUSED_PAD src0_sel:WORD_1 src1_sel:DWORD
	v_add3_u32 v180, v187, v180, s69
	v_pk_fma_f32 v[166:167], v[80:81], v[186:187], v[166:167] op_sel_hi:[1,0,1]
	v_pk_fma_f32 v[174:175], v[186:187], v[92:93], v[174:175] op_sel_hi:[0,1,1]
	v_pk_fma_f32 v[176:177], v[186:187], v[104:105], v[176:177] op_sel_hi:[0,1,1]
	v_pk_fma_f32 v[178:179], v[186:187], v[116:117], v[178:179] op_sel_hi:[0,1,1]
	v_and_b32_e32 v181, 0xffff0000, v181
	v_and_b32_e32 v182, 0xffff0000, v182
	v_pk_fma_f32 v[166:167], v[16:17], v[186:187], v[166:167] op_sel:[0,1,0]
	v_pk_fma_f32 v[174:175], v[186:187], v[30:31], v[174:175] op_sel:[1,0,0]
	v_pk_fma_f32 v[176:177], v[186:187], v[46:47], v[176:177] op_sel:[1,0,0]
	v_pk_fma_f32 v[178:179], v[186:187], v[62:63], v[178:179] op_sel:[1,0,0]
	v_and_b32_sdwa v187, v124, v232 dst_sel:DWORD dst_unused:UNUSED_PAD src0_sel:WORD_1 src1_sel:DWORD
	v_or_b32_sdwa v181, v181, v180 dst_sel:DWORD dst_unused:UNUSED_PAD src0_sel:DWORD src1_sel:WORD_1
	v_or_b32_sdwa v180, v182, v190 dst_sel:DWORD dst_unused:UNUSED_PAD src0_sel:DWORD src1_sel:WORD_1
	v_and_b32_sdwa v190, v121, v232 dst_sel:DWORD dst_unused:UNUSED_PAD src0_sel:WORD_1 src1_sel:DWORD
	v_and_b32_sdwa v191, v120, v232 dst_sel:DWORD dst_unused:UNUSED_PAD src0_sel:WORD_1 src1_sel:DWORD
	v_add3_u32 v182, v162, v185, s69
	v_add3_u32 v183, v163, v184, s69
	v_add3_u32 v184, v127, v188, s69
	v_add3_u32 v185, v126, v189, s69
	v_and_b32_sdwa v186, v125, v232 dst_sel:DWORD dst_unused:UNUSED_PAD src0_sel:WORD_1 src1_sel:DWORD
	v_and_b32_e32 v184, 0xffff0000, v184
	v_and_b32_e32 v185, 0xffff0000, v185
	v_add3_u32 v188, v124, v187, s69
	v_add3_u32 v187, v121, v190, s69
	v_add3_u32 v189, v120, v191, s69
	v_or_b32_sdwa v183, v184, v183 dst_sel:DWORD dst_unused:UNUSED_PAD src0_sel:DWORD src1_sel:WORD_1
	v_or_b32_sdwa v182, v185, v182 dst_sel:DWORD dst_unused:UNUSED_PAD src0_sel:DWORD src1_sel:WORD_1
	v_pk_mul_f32 v[184:185], v[126:127], v[24:25] op_sel_hi:[0,1]
	v_add3_u32 v186, v125, v186, s69
	v_and_b32_e32 v187, 0xffff0000, v187
	v_and_b32_e32 v189, 0xffff0000, v189
	global_store_dwordx2 v[84:85], v[180:181], off
	v_mov_b32_e32 v180, v124
	v_mov_b32_e32 v181, v120
	v_or_b32_sdwa v187, v187, v186 dst_sel:DWORD dst_unused:UNUSED_PAD src0_sel:DWORD src1_sel:WORD_1
	v_or_b32_sdwa v186, v189, v188 dst_sel:DWORD dst_unused:UNUSED_PAD src0_sel:DWORD src1_sel:WORD_1
	v_mov_b32_e32 v188, v120
	v_mov_b32_e32 v189, v124
	v_pk_fma_f32 v[184:185], v[162:163], v[26:27], v[184:185] op_sel_hi:[0,1,1]
	global_store_dwordx2 v[84:85], v[182:183], off offset:512
	v_pk_mul_f32 v[182:183], v[180:181], v[28:29]
	v_pk_fma_f32 v[166:167], v[22:23], v[164:165], v[166:167] op_sel:[0,1,0]
	v_pk_fma_f32 v[184:185], v[162:163], v[18:19], v[184:185] op_sel:[1,0,0]
	v_pk_fma_f32 v[182:183], v[188:189], v[38:39], v[182:183]
	v_pk_add_f32 v[166:167], v[166:167], 0 op_sel_hi:[1,0]
	v_pk_fma_f32 v[184:185], v[126:127], v[134:135], v[184:185] op_sel:[1,0,0]
	v_pk_fma_f32 v[182:183], v[124:125], v[136:137], v[182:183] op_sel:[1,0,0]
	v_pk_add_f32 v[166:167], v[166:167], v[184:185]
	v_pk_fma_f32 v[182:183], v[120:121], v[82:83], v[182:183] op_sel:[1,0,0]
	v_mov_b32_e32 v184, v96
	v_mov_b32_e32 v185, v108
	global_store_dwordx2 v[84:85], v[186:187], off offset:1024
	v_pk_add_f32 v[166:167], v[166:167], v[182:183]
	v_mov_b32_e32 v182, v108
	v_mov_b32_e32 v183, v96
	v_pk_mul_f32 v[186:187], v[184:185], v[76:77]
	v_pk_fma_f32 v[174:175], v[164:165], v[32:33], v[174:175] op_sel:[1,0,0]
	v_pk_fma_f32 v[186:187], v[182:183], v[138:139], v[186:187]
	v_pk_add_f32 v[174:175], v[174:175], 0 op_sel_hi:[1,0]
	v_pk_fma_f32 v[186:187], v[96:97], v[140:141], v[186:187] op_sel:[1,0,0]
	v_pk_fma_f32 v[176:177], v[164:165], v[48:49], v[176:177] op_sel:[1,0,0]
	v_pk_fma_f32 v[186:187], v[108:109], v[86:87], v[186:187] op_sel:[1,0,0]
	v_pk_add_f32 v[176:177], v[176:177], 0 op_sel_hi:[1,0]
	v_pk_add_f32 v[166:167], v[166:167], v[186:187]
	ds_bpermute_b32 v186, v168, v166
	ds_bpermute_b32 v187, v168, v167
	v_pk_fma_f32 v[164:165], v[164:165], v[64:65], v[178:179] op_sel:[1,0,0]
	v_pk_mul_f32 v[178:179], v[126:127], v[72:73] op_sel_hi:[0,1]
	v_pk_fma_f32 v[178:179], v[162:163], v[74:75], v[178:179] op_sel_hi:[0,1,1]
	v_pk_add_f32 v[164:165], v[164:165], 0 op_sel_hi:[1,0]
	s_waitcnt lgkmcnt(0)
	v_pk_add_f32 v[166:167], v[166:167], v[186:187]
	ds_bpermute_b32 v186, v169, v166
	ds_bpermute_b32 v187, v169, v167
	s_waitcnt lgkmcnt(0)
	v_pk_add_f32 v[166:167], v[166:167], v[186:187]
	ds_bpermute_b32 v186, v170, v166
	ds_bpermute_b32 v187, v170, v167
	s_waitcnt lgkmcnt(0)
	v_pk_add_f32 v[166:167], v[166:167], v[186:187]
	ds_bpermute_b32 v186, v171, v166
	ds_bpermute_b32 v187, v171, v167
	s_waitcnt lgkmcnt(0)
	v_pk_add_f32 v[166:167], v[166:167], v[186:187]
	ds_bpermute_b32 v186, v172, v166
	ds_bpermute_b32 v187, v172, v167
	s_waitcnt lgkmcnt(0)
	v_pk_add_f32 v[166:167], v[166:167], v[186:187]
	v_pk_mul_f32 v[186:187], v[126:127], v[40:41] op_sel_hi:[0,1]
	v_pk_fma_f32 v[186:187], v[162:163], v[42:43], v[186:187] op_sel_hi:[0,1,1]
	v_pk_fma_f32 v[186:187], v[162:163], v[34:35], v[186:187] op_sel:[1,0,0]
	s_nop 0
	v_pk_fma_f32 v[186:187], v[126:127], v[78:79], v[186:187] op_sel:[1,0,0]
	s_nop 0
	v_pk_add_f32 v[174:175], v[174:175], v[186:187]
	v_pk_mul_f32 v[186:187], v[180:181], v[44:45]
	s_nop 0
	v_pk_fma_f32 v[186:187], v[188:189], v[54:55], v[186:187]
	s_nop 0
	v_pk_fma_f32 v[186:187], v[124:125], v[142:143], v[186:187] op_sel:[1,0,0]
	s_nop 0
	v_pk_fma_f32 v[186:187], v[120:121], v[94:95], v[186:187] op_sel:[1,0,0]
	s_nop 0
	v_pk_add_f32 v[174:175], v[174:175], v[186:187]
	v_pk_mul_f32 v[186:187], v[184:185], v[88:89]
	s_nop 0
	v_pk_fma_f32 v[186:187], v[182:183], v[144:145], v[186:187]
	s_nop 0
	v_pk_fma_f32 v[186:187], v[96:97], v[146:147], v[186:187] op_sel:[1,0,0]
	s_nop 0
	v_pk_fma_f32 v[186:187], v[108:109], v[98:99], v[186:187] op_sel:[1,0,0]
	s_nop 0
	v_pk_add_f32 v[174:175], v[174:175], v[186:187]
	ds_bpermute_b32 v186, v168, v174
	ds_bpermute_b32 v187, v168, v175
	s_waitcnt lgkmcnt(0)
	v_pk_add_f32 v[174:175], v[174:175], v[186:187]
	ds_bpermute_b32 v186, v169, v174
	ds_bpermute_b32 v187, v169, v175
	s_waitcnt lgkmcnt(0)
	v_pk_add_f32 v[174:175], v[174:175], v[186:187]
	ds_bpermute_b32 v186, v170, v174
	ds_bpermute_b32 v187, v170, v175
	s_waitcnt lgkmcnt(0)
	v_pk_add_f32 v[174:175], v[174:175], v[186:187]
	ds_bpermute_b32 v186, v171, v174
	ds_bpermute_b32 v187, v171, v175
	s_waitcnt lgkmcnt(0)
	v_pk_add_f32 v[174:175], v[174:175], v[186:187]
	v_pk_mul_f32 v[186:187], v[126:127], v[56:57] op_sel_hi:[0,1]
	v_pk_fma_f32 v[186:187], v[162:163], v[58:59], v[186:187] op_sel_hi:[0,1,1]
	v_pk_fma_f32 v[186:187], v[162:163], v[50:51], v[186:187] op_sel:[1,0,0]
	v_pk_fma_f32 v[162:163], v[162:163], v[66:67], v[178:179] op_sel:[1,0,0]
	v_pk_fma_f32 v[186:187], v[126:127], v[90:91], v[186:187] op_sel:[1,0,0]
	v_and_b32_sdwa v178, v109, v232 dst_sel:DWORD dst_unused:UNUSED_PAD src0_sel:WORD_1 src1_sel:DWORD
	v_pk_add_f32 v[176:177], v[176:177], v[186:187]
	v_pk_mul_f32 v[186:187], v[180:181], v[60:61]
	v_and_b32_sdwa v179, v108, v232 dst_sel:DWORD dst_unused:UNUSED_PAD src0_sel:WORD_1 src1_sel:DWORD
	v_pk_fma_f32 v[186:187], v[188:189], v[70:71], v[186:187]
	v_add3_u32 v178, v109, v178, s69
	v_pk_fma_f32 v[186:187], v[124:125], v[148:149], v[186:187] op_sel:[1,0,0]
	v_add3_u32 v190, v108, v179, s69
	v_pk_fma_f32 v[186:187], v[120:121], v[106:107], v[186:187] op_sel:[1,0,0]
	v_and_b32_e32 v191, 0xffff0000, v178
	v_pk_add_f32 v[176:177], v[176:177], v[186:187]
	v_pk_mul_f32 v[186:187], v[184:185], v[100:101]
	v_pk_mul_f32 v[178:179], v[180:181], v[14:15]
	v_pk_fma_f32 v[186:187], v[182:183], v[150:151], v[186:187]
	v_pk_fma_f32 v[178:179], v[188:189], v[160:161], v[178:179]
	v_pk_fma_f32 v[186:187], v[96:97], v[152:153], v[186:187] op_sel:[1,0,0]
	v_pk_fma_f32 v[124:125], v[124:125], v[154:155], v[178:179] op_sel:[1,0,0]
	v_pk_fma_f32 v[186:187], v[108:109], v[110:111], v[186:187] op_sel:[1,0,0]
	v_pk_fma_f32 v[120:121], v[120:121], v[118:119], v[124:125] op_sel:[1,0,0]
	v_pk_mul_f32 v[124:125], v[184:185], v[112:113]
	v_pk_add_f32 v[176:177], v[176:177], v[186:187]
	v_and_b32_sdwa v186, v97, v232 dst_sel:DWORD dst_unused:UNUSED_PAD src0_sel:WORD_1 src1_sel:DWORD
	v_and_b32_sdwa v187, v96, v232 dst_sel:DWORD dst_unused:UNUSED_PAD src0_sel:WORD_1 src1_sel:DWORD
	v_pk_fma_f32 v[162:163], v[126:127], v[102:103], v[162:163] op_sel:[1,0,0]
	v_pk_fma_f32 v[124:125], v[182:183], v[156:157], v[124:125]
	v_add3_u32 v187, v96, v187, s69
	v_add3_u32 v186, v97, v186, s69
	v_pk_add_f32 v[162:163], v[164:165], v[162:163]
	v_pk_fma_f32 v[96:97], v[96:97], v[158:159], v[124:125] op_sel:[1,0,0]
	v_pk_add_f32 v[120:121], v[162:163], v[120:121]
	v_pk_fma_f32 v[96:97], v[108:109], v[122:123], v[96:97] op_sel:[1,0,0]
	ds_bpermute_b32 v164, v168, v176
	v_pk_add_f32 v[96:97], v[120:121], v[96:97]
	ds_bpermute_b32 v165, v168, v177
	ds_bpermute_b32 v108, v168, v96
	ds_bpermute_b32 v109, v168, v97
	ds_bpermute_b32 v120, v172, v174
	ds_bpermute_b32 v121, v172, v175
	s_waitcnt lgkmcnt(4)
	v_pk_add_f32 v[124:125], v[176:177], v[164:165]
	ds_bpermute_b32 v162, v169, v124
	s_waitcnt lgkmcnt(3)
	v_pk_add_f32 v[96:97], v[96:97], v[108:109]
	ds_bpermute_b32 v163, v169, v125
	ds_bpermute_b32 v108, v169, v96
	ds_bpermute_b32 v109, v169, v97
	ds_bpermute_b32 v126, v173, v166
	ds_bpermute_b32 v127, v173, v167
	s_waitcnt lgkmcnt(4)
	v_pk_add_f32 v[124:125], v[124:125], v[162:163]
	ds_bpermute_b32 v162, v170, v124
	s_waitcnt lgkmcnt(3)
	v_pk_add_f32 v[108:109], v[96:97], v[108:109]
	ds_bpermute_b32 v163, v170, v125
	ds_bpermute_b32 v164, v170, v108
	ds_bpermute_b32 v165, v170, v109
	v_pk_add_f32 v[96:97], v[174:175], v[120:121]
	v_and_b32_e32 v174, 0xffff0000, v190
	s_waitcnt lgkmcnt(2)
	v_pk_add_f32 v[120:121], v[124:125], v[162:163]
	ds_bpermute_b32 v124, v171, v120
	s_waitcnt lgkmcnt(1)
	v_pk_add_f32 v[162:163], v[108:109], v[164:165]
	ds_bpermute_b32 v125, v171, v121
	ds_bpermute_b32 v164, v171, v162
	ds_bpermute_b32 v165, v171, v163
	ds_bpermute_b32 v108, v173, v96
	ds_bpermute_b32 v109, v173, v97
	s_waitcnt lgkmcnt(4)
	v_pk_add_f32 v[120:121], v[120:121], v[124:125]
	ds_bpermute_b32 v124, v172, v120
	s_waitcnt lgkmcnt(3)
	v_pk_add_f32 v[162:163], v[162:163], v[164:165]
	ds_bpermute_b32 v125, v172, v121
	ds_bpermute_b32 v164, v172, v162
	ds_bpermute_b32 v165, v172, v163
	v_or_b32_sdwa v175, v191, v186 dst_sel:DWORD dst_unused:UNUSED_PAD src0_sel:DWORD src1_sel:WORD_1
	v_or_b32_sdwa v174, v174, v187 dst_sel:DWORD dst_unused:UNUSED_PAD src0_sel:DWORD src1_sel:WORD_1
	s_waitcnt lgkmcnt(2)
	v_pk_add_f32 v[120:121], v[120:121], v[124:125]
	ds_bpermute_b32 v124, v173, v120
	s_waitcnt lgkmcnt(1)
	v_pk_add_f32 v[162:163], v[162:163], v[164:165]
	ds_bpermute_b32 v125, v173, v121
	ds_bpermute_b32 v164, v173, v162
	ds_bpermute_b32 v165, v173, v163
	global_store_dwordx2 v[84:85], v[174:175], off offset:1536
	s_and_saveexec_b64 s[8:9], vcc
	s_cbranch_execz .LBB0_86
	v_readlane_b32 s10, v253, 28
	v_lshlrev_b64 v[84:85], 5, v[128:129]
	v_readlane_b32 s11, v253, 29
	v_pk_add_f32 v[174:175], v[166:167], v[126:127]
	v_pk_add_f32 v[176:177], v[96:97], v[108:109]
	v_lshl_add_u64 v[84:85], s[10:11], 0, v[84:85]
	s_waitcnt lgkmcnt(2)
	v_pk_add_f32 v[124:125], v[120:121], v[124:125]
	s_waitcnt lgkmcnt(0)
	v_pk_add_f32 v[126:127], v[162:163], v[164:165]
	global_store_dwordx4 v[84:85], v[174:177], off
	global_store_dwordx4 v[84:85], v[124:127], off offset:16
	s_branch .LBB0_86

.LBB0_837:
	s_or_b64 exec, exec, s[2:3]
	v_mov_b32_e32 v0, v216
	s_barrier
	v_readlane_b32 s2, v253, 8
	v_ashrrev_i32_e32 v1, 6, v0
	s_waitcnt vmcnt(30)
	v_add_u32_e32 v16, s2, v1
	s_movk_i32 s2, 0x4480
	v_cmp_gt_i32_e32 vcc, s2, v16
	s_and_saveexec_b64 s[2:3], vcc
	s_movk_i32 s8, 0x447f
	s_cbranch_execz .LBB0_840
	v_readlane_b32 s4, v255, 26
	v_lshlrev_b32_e32 v0, 2, v0
	v_readlane_b32 s5, v255, 27
	s_add_u32 s4, s40, s4
	s_waitcnt vmcnt(29)
	v_and_b32_e32 v17, 0xfc, v0
	s_addc_u32 s5, s41, s5
	v_lshlrev_b32_e32 v200, 2, v17
	global_load_dwordx4 v[0:3], v200, s[4:5]
	global_load_dwordx4 v[4:7], v200, s[4:5] offset:1024
	global_load_dwordx4 v[8:11], v200, s[4:5] offset:2048
	global_load_dwordx4 v[12:15], v200, s[4:5] offset:3072
	v_cmp_lt_i32_e32 vcc, v227, v219
	v_readlane_b32 s4, v253, 4
	s_waitcnt vmcnt(32)
	v_mov_b32_e32 v19, v201
	v_cndmask_b32_e32 v18, v218, v227, vcc
	v_cmp_lt_i32_e32 vcc, v225, v219
	s_waitcnt vmcnt(27)
	v_lshlrev_b32_e32 v24, 2, v18
	v_lshlrev_b32_e32 v18, 1, v17
	v_cndmask_b32_e32 v20, v218, v225, vcc
	v_cmp_lt_i32_e32 vcc, v223, v219
	v_readlane_b32 s5, v253, 5
	s_waitcnt vmcnt(25)
	v_lshlrev_b32_e32 v25, 2, v20
	v_cndmask_b32_e32 v21, v218, v223, vcc
	v_cmp_lt_i32_e32 vcc, v222, v219
	v_lshl_add_u64 v[18:19], s[4:5], 0, v[18:19]
	v_readlane_b32 s4, v253, 6
	v_cndmask_b32_e32 v22, v218, v222, vcc
	v_cmp_lt_i32_e32 vcc, v221, v219
	v_readlane_b32 s5, v253, 7
	v_lshlrev_b32_e32 v26, 2, v21
	v_cndmask_b32_e32 v23, v218, v221, vcc
	v_cmp_lt_i32_e32 vcc, v220, v219
	v_lshlrev_b32_e32 v27, 2, v22
	s_waitcnt vmcnt(24)
	v_lshlrev_b32_e32 v28, 2, v23
	s_waitcnt vmcnt(23)
	v_cndmask_b32_e32 v29, v218, v220, vcc
	v_lshlrev_b32_e32 v29, 2, v29
	v_lshl_add_u64 v[20:21], s[4:5], 0, v[200:201]
	s_mov_b64 s[4:5], 0
	s_waitcnt vmcnt(3)
	v_mov_b32_e32 v22, v1
	v_mov_b32_e32 v23, v3
	v_mov_b32_e32 v1, v2
	s_waitcnt vmcnt(2)
	v_mov_b32_e32 v2, v5
	v_mov_b32_e32 v3, v7
	v_mov_b32_e32 v5, v6
	s_waitcnt vmcnt(1)
	v_mov_b32_e32 v6, v9
	v_mov_b32_e32 v7, v11
	v_mov_b32_e32 v9, v10
	s_waitcnt vmcnt(0)
	v_mov_b32_e32 v10, v13
	v_mov_b32_e32 v11, v15
	v_mov_b32_e32 v13, v14
	v_mov_b32_e32 v116, v16
	v_ashrrev_i32_e32 v117, 31, v116
	v_lshlrev_b64 v[116:117], 12, v[116:117]
	v_lshl_add_u64 v[116:117], v[20:21], 0, v[116:117]
	global_load_dwordx4 v[100:103], v[116:117], off
	global_load_dwordx4 v[104:107], v[116:117], off offset:1024
	global_load_dwordx4 v[108:111], v[116:117], off offset:2048
	global_load_dwordx4 v[112:115], v[116:117], off offset:3072
.LBB0_839:
	v_ashrrev_i32_e32 v17, 31, v16
	v_lshlrev_b64 v[14:15], 12, v[16:17]
	v_lshl_add_u64 v[38:39], v[20:21], 0, v[14:15]
	s_waitcnt vmcnt(0)
	v_mov_b32_e32 v30, v100
	v_mov_b32_e32 v31, v101
	v_mov_b32_e32 v32, v102
	v_mov_b32_e32 v33, v103
	v_mov_b32_e32 v34, v104
	v_mov_b32_e32 v35, v105
	v_mov_b32_e32 v36, v106
	v_mov_b32_e32 v37, v107
	v_lshlrev_b64 v[14:15], 11, v[16:17]
	v_lshl_add_u64 v[14:15], v[18:19], 0, v[14:15]
	v_add_u32_e32 v16, s81, v16
	v_mov_b32_e32 v42, v30
	v_mov_b32_e32 v44, v31
	v_mov_b32_e32 v40, v30
	v_mov_b32_e32 v30, v31
	v_mov_b32_e32 v31, v35
	v_mov_b32_e32 v41, v34
	v_pk_mul_f32 v[30:31], v[30:31], v[30:31]
	v_mov_b32_e32 v43, v32
	v_pk_fma_f32 v[30:31], v[40:41], v[40:41], v[30:31]
	v_mov_b32_e32 v40, v32
	v_mov_b32_e32 v41, v36
	v_mov_b32_e32 v45, v33
	v_pk_fma_f32 v[30:31], v[40:41], v[40:41], v[30:31]
	v_mov_b32_e32 v32, v33
	v_mov_b32_e32 v33, v37
	v_pk_fma_f32 v[46:47], v[32:33], v[32:33], v[30:31]
	v_mov_b32_e32 v30, v108
	v_mov_b32_e32 v31, v109
	v_mov_b32_e32 v32, v110
	v_mov_b32_e32 v33, v111
	v_mov_b32_e32 v48, v34
	v_mov_b32_e32 v38, v112
	v_mov_b32_e32 v39, v113
	v_mov_b32_e32 v40, v114
	v_mov_b32_e32 v41, v115
	v_min_i32_e32 v116, s8, v16
	v_ashrrev_i32_e32 v117, 31, v116
	v_lshlrev_b64 v[116:117], 12, v[116:117]
	v_lshl_add_u64 v[116:117], v[20:21], 0, v[116:117]
	global_load_dwordx4 v[100:103], v[116:117], off
	global_load_dwordx4 v[104:107], v[116:117], off offset:1024
	global_load_dwordx4 v[108:111], v[116:117], off offset:2048
	global_load_dwordx4 v[112:115], v[116:117], off offset:3072
	v_mov_b32_e32 v49, v36
	v_mov_b32_e32 v36, v35
	v_add_f32_e32 v17, v46, v47
	v_mov_b32_e32 v34, v30
	v_mov_b32_e32 v50, v31
	v_mov_b32_e32 v52, v30
	v_mov_b32_e32 v30, v31
	v_mov_b32_e32 v31, v39
	v_mov_b32_e32 v53, v38
	v_pk_mul_f32 v[30:31], v[30:31], v[30:31]
	v_mov_b32_e32 v35, v32
	v_pk_fma_f32 v[30:31], v[52:53], v[52:53], v[30:31]
	v_mov_b32_e32 v52, v32
	v_mov_b32_e32 v53, v40
	v_mov_b32_e32 v51, v33
	v_pk_fma_f32 v[30:31], v[52:53], v[52:53], v[30:31]
	v_mov_b32_e32 v32, v33
	v_mov_b32_e32 v33, v41
	v_pk_fma_f32 v[30:31], v[32:33], v[32:33], v[30:31]
	s_nop 0
	v_add_f32_e32 v17, v17, v30
	v_add_f32_e32 v17, v17, v31
	ds_bpermute_b32 v30, v24, v17
	s_waitcnt lgkmcnt(0)
	v_add_f32_e32 v17, v17, v30
	ds_bpermute_b32 v30, v25, v17
	s_waitcnt lgkmcnt(0)
	v_add_f32_e32 v17, v17, v30
	ds_bpermute_b32 v30, v26, v17
	s_waitcnt lgkmcnt(0)
	v_add_f32_e32 v17, v17, v30
	ds_bpermute_b32 v30, v27, v17
	s_waitcnt lgkmcnt(0)
	v_add_f32_e32 v17, v17, v30
	ds_bpermute_b32 v30, v28, v17
	s_waitcnt lgkmcnt(0)
	v_add_f32_e32 v17, v17, v30
	ds_bpermute_b32 v30, v29, v17
	s_waitcnt lgkmcnt(0)
	v_add_f32_e32 v17, v17, v30
	v_fmamk_f32 v17, v17, 0x3a800000, v217
	v_cmp_gt_f32_e32 vcc, s75, v17
	v_mul_f32_e32 v30, 0x4b800000, v17
	s_nop 0
	v_cndmask_b32_e32 v17, v17, v30, vcc
	v_rsq_f32_e32 v17, v17
	s_nop 0
	v_mul_f32_e32 v30, 0x45800000, v17
	v_cndmask_b32_e32 v30, v17, v30, vcc
	v_pk_mul_f32 v[46:47], v[2:3], v[30:31] op_sel_hi:[1,0]
	v_pk_mul_f32 v[32:33], v[0:1], v[30:31] op_sel_hi:[1,0]
	v_pk_mul_f32 v[36:37], v[36:37], v[46:47]
	v_pk_mul_f32 v[46:47], v[8:9], v[30:31] op_sel_hi:[1,0]
	v_pk_mul_f32 v[32:33], v[42:43], v[32:33]
	v_pk_mul_f32 v[42:43], v[22:23], v[30:31] op_sel_hi:[1,0]
	v_pk_mul_f32 v[34:35], v[34:35], v[46:47]
	v_pk_mul_f32 v[46:47], v[6:7], v[30:31] op_sel_hi:[1,0]
	v_pk_mul_f32 v[42:43], v[44:45], v[42:43]
	v_pk_mul_f32 v[46:47], v[50:51], v[46:47]
	v_mov_b32_e32 v50, v38
	v_and_b32_sdwa v17, v33, v232 dst_sel:DWORD dst_unused:UNUSED_PAD src0_sel:WORD_1 src1_sel:DWORD
	v_and_b32_sdwa v38, v32, v232 dst_sel:DWORD dst_unused:UNUSED_PAD src0_sel:WORD_1 src1_sel:DWORD
	v_add3_u32 v32, v32, v38, s69
	v_add3_u32 v17, v33, v17, s69
	v_and_b32_sdwa v33, v43, v232 dst_sel:DWORD dst_unused:UNUSED_PAD src0_sel:WORD_1 src1_sel:DWORD
	v_and_b32_sdwa v38, v42, v232 dst_sel:DWORD dst_unused:UNUSED_PAD src0_sel:WORD_1 src1_sel:DWORD
	v_add3_u32 v33, v43, v33, s69
	v_add3_u32 v38, v42, v38, s69
	v_and_b32_e32 v33, 0xffff0000, v33
	v_and_b32_e32 v38, 0xffff0000, v38
	v_pk_mul_f32 v[44:45], v[4:5], v[30:31] op_sel_hi:[1,0]
	v_or_b32_sdwa v33, v33, v17 dst_sel:DWORD dst_unused:UNUSED_PAD src0_sel:DWORD src1_sel:WORD_1
	v_or_b32_sdwa v32, v38, v32 dst_sel:DWORD dst_unused:UNUSED_PAD src0_sel:DWORD src1_sel:WORD_1
	v_pk_mul_f32 v[44:45], v[48:49], v[44:45]
	global_store_dwordx2 v[14:15], v[32:33], off
	v_and_b32_sdwa v33, v37, v232 dst_sel:DWORD dst_unused:UNUSED_PAD src0_sel:WORD_1 src1_sel:DWORD
	v_and_b32_sdwa v38, v36, v232 dst_sel:DWORD dst_unused:UNUSED_PAD src0_sel:WORD_1 src1_sel:DWORD
	v_and_b32_sdwa v17, v45, v232 dst_sel:DWORD dst_unused:UNUSED_PAD src0_sel:WORD_1 src1_sel:DWORD
	v_and_b32_sdwa v32, v44, v232 dst_sel:DWORD dst_unused:UNUSED_PAD src0_sel:WORD_1 src1_sel:DWORD
	v_add3_u32 v33, v37, v33, s69
	v_add3_u32 v36, v36, v38, s69
	v_add3_u32 v32, v44, v32, s69
	v_add3_u32 v17, v45, v17, s69
	v_and_b32_e32 v33, 0xffff0000, v33
	v_and_b32_e32 v36, 0xffff0000, v36
	v_or_b32_sdwa v33, v33, v17 dst_sel:DWORD dst_unused:UNUSED_PAD src0_sel:DWORD src1_sel:WORD_1
	v_or_b32_sdwa v32, v36, v32 dst_sel:DWORD dst_unused:UNUSED_PAD src0_sel:DWORD src1_sel:WORD_1
	global_store_dwordx2 v[14:15], v[32:33], off offset:512
	v_and_b32_sdwa v32, v34, v232 dst_sel:DWORD dst_unused:UNUSED_PAD src0_sel:WORD_1 src1_sel:DWORD
	v_add3_u32 v32, v34, v32, s69
	v_and_b32_sdwa v33, v47, v232 dst_sel:DWORD dst_unused:UNUSED_PAD src0_sel:WORD_1 src1_sel:DWORD
	v_and_b32_sdwa v34, v46, v232 dst_sel:DWORD dst_unused:UNUSED_PAD src0_sel:WORD_1 src1_sel:DWORD
	v_and_b32_sdwa v17, v35, v232 dst_sel:DWORD dst_unused:UNUSED_PAD src0_sel:WORD_1 src1_sel:DWORD
	v_add3_u32 v33, v47, v33, s69
	v_add3_u32 v34, v46, v34, s69
	v_pk_mul_f32 v[48:49], v[12:13], v[30:31] op_sel_hi:[1,0]
	v_mov_b32_e32 v51, v40
	v_pk_mul_f32 v[30:31], v[10:11], v[30:31] op_sel_hi:[1,0]
	v_mov_b32_e32 v40, v39
	v_add3_u32 v17, v35, v17, s69
	v_and_b32_e32 v33, 0xffff0000, v33
	v_and_b32_e32 v34, 0xffff0000, v34
	v_pk_mul_f32 v[30:31], v[40:41], v[30:31]
	v_or_b32_sdwa v33, v33, v17 dst_sel:DWORD dst_unused:UNUSED_PAD src0_sel:DWORD src1_sel:WORD_1
	v_or_b32_sdwa v32, v34, v32 dst_sel:DWORD dst_unused:UNUSED_PAD src0_sel:DWORD src1_sel:WORD_1
	v_pk_mul_f32 v[48:49], v[50:51], v[48:49]
	global_store_dwordx2 v[14:15], v[32:33], off offset:1024
	v_and_b32_sdwa v33, v31, v232 dst_sel:DWORD dst_unused:UNUSED_PAD src0_sel:WORD_1 src1_sel:DWORD
	v_and_b32_sdwa v34, v30, v232 dst_sel:DWORD dst_unused:UNUSED_PAD src0_sel:WORD_1 src1_sel:DWORD
	v_and_b32_sdwa v17, v49, v232 dst_sel:DWORD dst_unused:UNUSED_PAD src0_sel:WORD_1 src1_sel:DWORD
	v_and_b32_sdwa v32, v48, v232 dst_sel:DWORD dst_unused:UNUSED_PAD src0_sel:WORD_1 src1_sel:DWORD
	v_add3_u32 v31, v31, v33, s69
	v_add3_u32 v30, v30, v34, s69
	v_add3_u32 v32, v48, v32, s69
	v_add3_u32 v17, v49, v17, s69
	v_and_b32_e32 v31, 0xffff0000, v31
	v_and_b32_e32 v30, 0xffff0000, v30
	v_cmp_lt_i32_e32 vcc, s8, v16
	v_or_b32_sdwa v31, v31, v17 dst_sel:DWORD dst_unused:UNUSED_PAD src0_sel:DWORD src1_sel:WORD_1
	v_or_b32_sdwa v30, v30, v32 dst_sel:DWORD dst_unused:UNUSED_PAD src0_sel:DWORD src1_sel:WORD_1
	s_or_b64 s[4:5], vcc, s[4:5]
	global_store_dwordx2 v[14:15], v[30:31], off offset:1536
	s_andn2_b64 exec, exec, s[4:5]
	s_cbranch_execnz .LBB0_839
